# attention loop: PV.2 MFMAs moved before the QK chain so the first post-barrier K fragment read has 6 MFMA slots of cover (with distance-7 prefetch), on top of v31
# baseline (speedup 1.0000x reference)
.Lattn_fx_loop:
	ds_read_b128 v[188:191], v209 offset:13376
	ds_read_b128 v[168:171], v209 offset:17984
	ds_read_b128 v[220:223], v187 offset:22528
	s_waitcnt lgkmcnt(6)
	v_mfma_f32_32x32x16_bf16 v[16:31], v[128:131], v[112:115], v[16:31]
	ds_read_b128 v[224:227], v187 offset:22560
	s_waitcnt vmcnt(0)
	ds_write_b128 v211, v[176:179] offset:45056
	s_and_saveexec_b64 s[42:43], s[36:37]
	s_cbranch_execz .Lattn_fx_w0
	ds_write_b128 v186, v[172:175] offset:45056
.Lattn_fx_w0:
	s_or_b64 exec, exec, s[42:43]
	ds_write_b128 v208, v[180:183] offset:58368
	v_exp_f32_e32 v48, v48
	v_exp_f32_e32 v49, v49
	v_exp_f32_e32 v50, v50
	s_waitcnt lgkmcnt(8)
	v_mfma_f32_32x32x16_bf16 v[32:47], v[132:135], v[112:115], v[32:47]
	ds_read_b128 v[128:131], v187 offset:22592
	global_load_dwordx4 v[176:179], v212, s[6:7]
	s_and_saveexec_b64 s[42:43], s[36:37]
	s_cbranch_execz .Lattn_fx_g1
	global_load_dwordx4 v[172:175], v214, s[6:7]
.Lattn_fx_g1:
	s_or_b64 exec, exec, s[42:43]
	global_load_dwordx4 v[180:183], v204, s[40:41]
	s_add_u32 s6, s6, 0x18000
	s_addc_u32 s7, s7, 0
	s_add_u32 s40, s40, 0x80
	s_addc_u32 s41, s41, 0
	v_exp_f32_e32 v51, v51
	v_exp_f32_e32 v52, v52
	v_exp_f32_e32 v53, v53
	s_waitcnt lgkmcnt(8)
	v_mfma_f32_32x32x16_bf16 v[16:31], v[136:139], v[116:119], v[16:31]
	ds_read_b128 v[132:135], v187 offset:22624
	v_exp_f32_e32 v54, v54
	v_exp_f32_e32 v55, v55
	v_cvt_pk_bf16_f32 v120, v48, v49
	v_cvt_pk_bf16_f32 v121, v50, v51
	s_waitcnt lgkmcnt(8)
	v_mfma_f32_32x32x16_bf16 v[32:47], v[140:143], v[116:119], v[32:47]
	ds_read_b128 v[136:139], v187 offset:22656
	v_cvt_pk_bf16_f32 v122, v52, v53
	v_cvt_pk_bf16_f32 v123, v54, v55
	v_exp_f32_e32 v56, v56
	v_exp_f32_e32 v57, v57
	s_waitcnt lgkmcnt(8)
	v_mfma_f32_32x32x16_bf16 v[16:31], v[188:191], v[120:123], v[16:31]
	ds_read_b128 v[140:143], v187 offset:22688
	v_exp_f32_e32 v58, v58
	v_exp_f32_e32 v59, v59
	v_add_f32_e32 v48, v64, v48
	v_add_f32_e32 v244, v244, v48
	s_waitcnt lgkmcnt(8)
	v_mfma_f32_32x32x16_bf16 v[32:47], v[168:171], v[120:123], v[32:47]
	ds_read_b128 v[188:191], v187 offset:29184
	v_exp_f32_e32 v60, v60
	v_exp_f32_e32 v61, v61
	v_add_f32_e32 v49, v65, v49
	v_add_f32_e32 v245, v245, v49
	s_waitcnt lgkmcnt(8)
	v_mfma_f32_32x32x16_bf16 v[96:111], v[220:223], v[164:167], v[0:15]
	ds_read_b128 v[168:171], v187 offset:29216
	v_exp_f32_e32 v62, v62
	v_exp_f32_e32 v63, v63
	v_add_f32_e32 v50, v66, v50
	v_add_f32_e32 v242, v242, v50
	s_waitcnt lgkmcnt(8)
	v_mfma_f32_32x32x16_bf16 v[96:111], v[224:227], v[144:147], v[96:111]
	ds_read_b128 v[220:223], v187 offset:29248
	v_cvt_pk_bf16_f32 v124, v56, v57
	v_cvt_pk_bf16_f32 v125, v58, v59
	v_cvt_pk_bf16_f32 v126, v60, v61
	v_cvt_pk_bf16_f32 v127, v62, v63
	v_add_f32_e32 v51, v67, v51
	v_add_f32_e32 v243, v243, v51
	s_waitcnt lgkmcnt(6)
	v_mfma_f32_32x32x16_bf16 v[96:111], v[128:131], v[148:151], v[96:111]
	ds_read_b128 v[224:227], v209 offset:13408
	v_add_f32_e32 v52, v68, v52
	v_add_f32_e32 v240, v240, v52
	v_add_f32_e32 v53, v69, v53
	v_add_f32_e32 v241, v241, v53
	v_add_f32_e32 v54, v70, v54
	v_add_f32_e32 v238, v238, v54
	s_waitcnt lgkmcnt(6)
	v_mfma_f32_32x32x16_bf16 v[96:111], v[132:135], v[152:155], v[96:111]
	ds_read_b128 v[128:131], v209 offset:18016
	v_add_f32_e32 v55, v71, v55
	v_add_f32_e32 v239, v239, v55
	v_add_f32_e32 v56, v72, v56
	v_add_f32_e32 v236, v236, v56
	v_add_f32_e32 v57, v73, v57
	v_add_f32_e32 v237, v237, v57
	s_waitcnt lgkmcnt(6)
	v_mfma_f32_32x32x16_bf16 v[96:111], v[136:139], v[156:159], v[96:111]
	ds_read_b128 v[132:135], v187 offset:29280
	v_add_f32_e32 v58, v74, v58
	v_add_f32_e32 v234, v234, v58
	v_add_f32_e32 v59, v75, v59
	v_add_f32_e32 v235, v235, v59
	v_add_f32_e32 v60, v76, v60
	v_add_f32_e32 v232, v232, v60
	s_waitcnt lgkmcnt(6)
	v_mfma_f32_32x32x16_bf16 v[96:111], v[140:143], v[160:163], v[96:111]
	ds_read_b128 v[136:139], v187 offset:29312
	v_add_f32_e32 v61, v77, v61
	v_add_f32_e32 v233, v233, v61
	v_add_f32_e32 v62, v78, v62
	v_add_f32_e32 v230, v230, v62
	s_waitcnt lgkmcnt(6)
	v_mfma_f32_32x32x16_bf16 v[80:95], v[188:191], v[164:167], v[0:15]
	ds_read_b128 v[140:143], v187 offset:29344
	v_add_f32_e32 v63, v79, v63
	v_add_f32_e32 v231, v231, v63
	s_waitcnt lgkmcnt(6)
	v_mfma_f32_32x32x16_bf16 v[80:95], v[168:171], v[144:147], v[80:95]
	ds_read_b128 v[188:191], v209 offset:35840
	v_exp_f32_e32 v96, v96
	v_exp_f32_e32 v97, v97
	v_exp_f32_e32 v98, v98
	s_waitcnt lgkmcnt(6)
	v_mfma_f32_32x32x16_bf16 v[80:95], v[220:223], v[148:151], v[80:95]
	ds_read_b128 v[168:171], v209 offset:40448
	v_exp_f32_e32 v99, v99
	v_exp_f32_e32 v100, v100
	v_exp_f32_e32 v101, v101
	s_waitcnt lgkmcnt(6)
	v_mfma_f32_32x32x16_bf16 v[16:31], v[224:227], v[124:127], v[16:31]
	ds_read_b128 v[220:223], v209 offset:35872
	v_exp_f32_e32 v102, v102
	v_exp_f32_e32 v103, v103
	v_cvt_pk_bf16_f32 v112, v96, v97
	v_cvt_pk_bf16_f32 v113, v98, v99
	s_waitcnt lgkmcnt(6)
	v_mfma_f32_32x32x16_bf16 v[32:47], v[128:131], v[124:127], v[32:47]
	ds_read_b128 v[224:227], v209 offset:40480
	v_cvt_pk_bf16_f32 v114, v100, v101
	v_cvt_pk_bf16_f32 v115, v102, v103
	v_exp_f32_e32 v104, v104
	v_exp_f32_e32 v105, v105
	s_waitcnt lgkmcnt(6)
	v_mfma_f32_32x32x16_bf16 v[80:95], v[132:135], v[152:155], v[80:95]
	v_exp_f32_e32 v106, v106
	v_exp_f32_e32 v107, v107
	v_exp_f32_e32 v108, v108
	s_waitcnt lgkmcnt(5)
	v_mfma_f32_32x32x16_bf16 v[80:95], v[136:139], v[156:159], v[80:95]
	v_exp_f32_e32 v109, v109
	v_exp_f32_e32 v110, v110
	v_exp_f32_e32 v111, v111
	s_waitcnt lgkmcnt(4)
	v_mfma_f32_32x32x16_bf16 v[80:95], v[140:143], v[160:163], v[80:95]
	v_cvt_pk_bf16_f32 v116, v104, v105
	v_cvt_pk_bf16_f32 v117, v106, v107
	v_cvt_pk_bf16_f32 v118, v108, v109
	v_cvt_pk_bf16_f32 v119, v110, v111
	s_waitcnt lgkmcnt(4)
	s_barrier
	ds_read_b128 v[128:131], v209 offset:35904
	ds_read_b128 v[132:135], v209 offset:40512
	ds_read_b128 v[136:139], v187 offset:45056
	s_waitcnt lgkmcnt(6)
	v_mfma_f32_32x32x16_bf16 v[16:31], v[188:191], v[112:115], v[16:31]
	ds_read_b128 v[140:143], v187 offset:45088
	s_waitcnt vmcnt(0)
	ds_write_b128 v211, v[176:179] offset:0
	s_and_saveexec_b64 s[42:43], s[36:37]
	s_cbranch_execz .Lattn_fx_w2
	ds_write_b128 v186, v[172:175] offset:0
.Lattn_fx_w2:
	s_or_b64 exec, exec, s[42:43]
	ds_write_b128 v208, v[180:183] offset:13312
	v_exp_f32_e32 v80, v80
	v_exp_f32_e32 v81, v81
	v_exp_f32_e32 v82, v82
	s_waitcnt lgkmcnt(8)
	v_mfma_f32_32x32x16_bf16 v[32:47], v[168:171], v[112:115], v[32:47]
	ds_read_b128 v[188:191], v187 offset:45120
	global_load_dwordx4 v[176:179], v212, s[6:7]
	s_and_saveexec_b64 s[42:43], s[36:37]
	s_cbranch_execz .Lattn_fx_g3
	global_load_dwordx4 v[172:175], v214, s[6:7]
.Lattn_fx_g3:
	s_or_b64 exec, exec, s[42:43]
	global_load_dwordx4 v[180:183], v204, s[40:41]
	s_add_u32 s6, s6, 0x18000
	s_addc_u32 s7, s7, 0
	s_add_u32 s40, s40, 0x80
	s_addc_u32 s41, s41, 0
	v_exp_f32_e32 v83, v83
	v_exp_f32_e32 v84, v84
	v_exp_f32_e32 v85, v85
	s_waitcnt lgkmcnt(8)
	v_mfma_f32_32x32x16_bf16 v[16:31], v[220:223], v[116:119], v[16:31]
	ds_read_b128 v[168:171], v187 offset:45152
	v_exp_f32_e32 v86, v86
	v_exp_f32_e32 v87, v87
	v_cvt_pk_bf16_f32 v120, v80, v81
	v_cvt_pk_bf16_f32 v121, v82, v83
	s_waitcnt lgkmcnt(8)
	v_mfma_f32_32x32x16_bf16 v[32:47], v[224:227], v[116:119], v[32:47]
	ds_read_b128 v[220:223], v187 offset:45184
	v_cvt_pk_bf16_f32 v122, v84, v85
	v_cvt_pk_bf16_f32 v123, v86, v87
	v_exp_f32_e32 v88, v88
	v_exp_f32_e32 v89, v89
	s_waitcnt lgkmcnt(8)
	v_mfma_f32_32x32x16_bf16 v[16:31], v[128:131], v[120:123], v[16:31]
	ds_read_b128 v[224:227], v187 offset:45216
	v_exp_f32_e32 v90, v90
	v_exp_f32_e32 v91, v91
	v_add_f32_e32 v80, v96, v80
	v_add_f32_e32 v244, v244, v80
	s_waitcnt lgkmcnt(8)
	v_mfma_f32_32x32x16_bf16 v[32:47], v[132:135], v[120:123], v[32:47]
	ds_read_b128 v[128:131], v187 offset:51712
	v_exp_f32_e32 v92, v92
	v_exp_f32_e32 v93, v93
	v_add_f32_e32 v81, v97, v81
	v_add_f32_e32 v245, v245, v81
	s_waitcnt lgkmcnt(8)
	v_mfma_f32_32x32x16_bf16 v[64:79], v[136:139], v[164:167], v[0:15]
	ds_read_b128 v[132:135], v187 offset:51744
	v_exp_f32_e32 v94, v94
	v_exp_f32_e32 v95, v95
	v_add_f32_e32 v82, v98, v82
	v_add_f32_e32 v242, v242, v82
	s_waitcnt lgkmcnt(8)
	v_mfma_f32_32x32x16_bf16 v[64:79], v[140:143], v[144:147], v[64:79]
	ds_read_b128 v[136:139], v187 offset:51776
	v_cvt_pk_bf16_f32 v124, v88, v89
	v_cvt_pk_bf16_f32 v125, v90, v91
	v_cvt_pk_bf16_f32 v126, v92, v93
	v_cvt_pk_bf16_f32 v127, v94, v95
	v_add_f32_e32 v83, v99, v83
	v_add_f32_e32 v243, v243, v83
	s_waitcnt lgkmcnt(6)
	v_mfma_f32_32x32x16_bf16 v[64:79], v[188:191], v[148:151], v[64:79]
	ds_read_b128 v[140:143], v209 offset:35936
	v_add_f32_e32 v84, v100, v84
	v_add_f32_e32 v240, v240, v84
	v_add_f32_e32 v85, v101, v85
	v_add_f32_e32 v241, v241, v85
	v_add_f32_e32 v86, v102, v86
	v_add_f32_e32 v238, v238, v86
	s_waitcnt lgkmcnt(6)
	v_mfma_f32_32x32x16_bf16 v[64:79], v[168:171], v[152:155], v[64:79]
	ds_read_b128 v[188:191], v209 offset:40544
	v_add_f32_e32 v87, v103, v87
	v_add_f32_e32 v239, v239, v87
	v_add_f32_e32 v88, v104, v88
	v_add_f32_e32 v236, v236, v88
	v_add_f32_e32 v89, v105, v89
	v_add_f32_e32 v237, v237, v89
	s_waitcnt lgkmcnt(6)
	v_mfma_f32_32x32x16_bf16 v[64:79], v[220:223], v[156:159], v[64:79]
	ds_read_b128 v[168:171], v187 offset:51808
	v_add_f32_e32 v90, v106, v90
	v_add_f32_e32 v234, v234, v90
	v_add_f32_e32 v91, v107, v91
	v_add_f32_e32 v235, v235, v91
	v_add_f32_e32 v92, v108, v92
	v_add_f32_e32 v232, v232, v92
	s_waitcnt lgkmcnt(6)
	v_mfma_f32_32x32x16_bf16 v[64:79], v[224:227], v[160:163], v[64:79]
	ds_read_b128 v[220:223], v187 offset:51840
	v_add_f32_e32 v93, v109, v93
	v_add_f32_e32 v233, v233, v93
	v_add_f32_e32 v94, v110, v94
	v_add_f32_e32 v230, v230, v94
	s_waitcnt lgkmcnt(6)
	v_mfma_f32_32x32x16_bf16 v[48:63], v[128:131], v[164:167], v[0:15]
	ds_read_b128 v[224:227], v187 offset:51872
	v_add_f32_e32 v95, v111, v95
	v_add_f32_e32 v231, v231, v95
	s_waitcnt lgkmcnt(6)
	v_mfma_f32_32x32x16_bf16 v[48:63], v[132:135], v[144:147], v[48:63]
	ds_read_b128 v[128:131], v209 offset:58368
	v_exp_f32_e32 v64, v64
	v_exp_f32_e32 v65, v65
	v_exp_f32_e32 v66, v66
	s_waitcnt lgkmcnt(6)
	v_mfma_f32_32x32x16_bf16 v[48:63], v[136:139], v[148:151], v[48:63]
	ds_read_b128 v[132:135], v209 offset:62976
	v_exp_f32_e32 v67, v67
	v_exp_f32_e32 v68, v68
	v_exp_f32_e32 v69, v69
	s_waitcnt lgkmcnt(6)
	v_mfma_f32_32x32x16_bf16 v[16:31], v[140:143], v[124:127], v[16:31]
	ds_read_b128 v[136:139], v209 offset:58400
	v_exp_f32_e32 v70, v70
	v_exp_f32_e32 v71, v71
	v_cvt_pk_bf16_f32 v112, v64, v65
	v_cvt_pk_bf16_f32 v113, v66, v67
	s_waitcnt lgkmcnt(6)
	v_mfma_f32_32x32x16_bf16 v[32:47], v[188:191], v[124:127], v[32:47]
	ds_read_b128 v[140:143], v209 offset:63008
	v_cvt_pk_bf16_f32 v114, v68, v69
	v_cvt_pk_bf16_f32 v115, v70, v71
	v_exp_f32_e32 v72, v72
	v_exp_f32_e32 v73, v73
	s_waitcnt lgkmcnt(6)
	v_mfma_f32_32x32x16_bf16 v[48:63], v[168:171], v[152:155], v[48:63]
	v_exp_f32_e32 v74, v74
	v_exp_f32_e32 v75, v75
	v_exp_f32_e32 v76, v76
	s_waitcnt lgkmcnt(5)
	v_mfma_f32_32x32x16_bf16 v[48:63], v[220:223], v[156:159], v[48:63]
	v_exp_f32_e32 v77, v77
	v_exp_f32_e32 v78, v78
	v_exp_f32_e32 v79, v79
	s_waitcnt lgkmcnt(4)
	v_mfma_f32_32x32x16_bf16 v[48:63], v[224:227], v[160:163], v[48:63]
	v_cvt_pk_bf16_f32 v116, v72, v73
	v_cvt_pk_bf16_f32 v117, v74, v75
	v_cvt_pk_bf16_f32 v118, v76, v77
	v_cvt_pk_bf16_f32 v119, v78, v79
	s_waitcnt lgkmcnt(4)
	s_barrier
	ds_read_b128 v[188:191], v209 offset:58432
	ds_read_b128 v[168:171], v209 offset:63040
	ds_read_b128 v[220:223], v187 offset:0
	s_waitcnt lgkmcnt(6)
	v_mfma_f32_32x32x16_bf16 v[16:31], v[128:131], v[112:115], v[16:31]
	ds_read_b128 v[224:227], v187 offset:32
	s_waitcnt vmcnt(0)
	ds_write_b128 v211, v[176:179] offset:22528
	s_and_saveexec_b64 s[42:43], s[36:37]
	s_cbranch_execz .Lattn_fx_w4
	ds_write_b128 v186, v[172:175] offset:22528
.Lattn_fx_w4:
	s_or_b64 exec, exec, s[42:43]
	ds_write_b128 v208, v[180:183] offset:35840
	v_exp_f32_e32 v48, v48
	v_exp_f32_e32 v49, v49
	v_exp_f32_e32 v50, v50
	s_waitcnt lgkmcnt(8)
	v_mfma_f32_32x32x16_bf16 v[32:47], v[132:135], v[112:115], v[32:47]
	ds_read_b128 v[128:131], v187 offset:64
	global_load_dwordx4 v[176:179], v212, s[6:7]
	s_and_saveexec_b64 s[42:43], s[36:37]
	s_cbranch_execz .Lattn_fx_g5
	global_load_dwordx4 v[172:175], v214, s[6:7]
.Lattn_fx_g5:
	s_or_b64 exec, exec, s[42:43]
	global_load_dwordx4 v[180:183], v204, s[40:41]
	s_add_u32 s6, s6, 0x18000
	s_addc_u32 s7, s7, 0
	s_add_u32 s40, s40, 0x80
	s_addc_u32 s41, s41, 0
	v_exp_f32_e32 v51, v51
	v_exp_f32_e32 v52, v52
	v_exp_f32_e32 v53, v53
	s_waitcnt lgkmcnt(8)
	v_mfma_f32_32x32x16_bf16 v[16:31], v[136:139], v[116:119], v[16:31]
	ds_read_b128 v[132:135], v187 offset:96
	v_exp_f32_e32 v54, v54
	v_exp_f32_e32 v55, v55
	v_cvt_pk_bf16_f32 v120, v48, v49
	v_cvt_pk_bf16_f32 v121, v50, v51
	s_waitcnt lgkmcnt(8)
	v_mfma_f32_32x32x16_bf16 v[32:47], v[140:143], v[116:119], v[32:47]
	ds_read_b128 v[136:139], v187 offset:128
	v_cvt_pk_bf16_f32 v122, v52, v53
	v_cvt_pk_bf16_f32 v123, v54, v55
	v_exp_f32_e32 v56, v56
	v_exp_f32_e32 v57, v57
	s_waitcnt lgkmcnt(8)
	v_mfma_f32_32x32x16_bf16 v[16:31], v[188:191], v[120:123], v[16:31]
	ds_read_b128 v[140:143], v187 offset:160
	v_exp_f32_e32 v58, v58
	v_exp_f32_e32 v59, v59
	v_add_f32_e32 v48, v64, v48
	v_add_f32_e32 v244, v244, v48
	s_waitcnt lgkmcnt(8)
	v_mfma_f32_32x32x16_bf16 v[32:47], v[168:171], v[120:123], v[32:47]
	ds_read_b128 v[188:191], v187 offset:6656
	v_exp_f32_e32 v60, v60
	v_exp_f32_e32 v61, v61
	v_add_f32_e32 v49, v65, v49
	v_add_f32_e32 v245, v245, v49
	s_waitcnt lgkmcnt(8)
	v_mfma_f32_32x32x16_bf16 v[96:111], v[220:223], v[164:167], v[0:15]
	ds_read_b128 v[168:171], v187 offset:6688
	v_exp_f32_e32 v62, v62
	v_exp_f32_e32 v63, v63
	v_add_f32_e32 v50, v66, v50
	v_add_f32_e32 v242, v242, v50
	s_waitcnt lgkmcnt(8)
	v_mfma_f32_32x32x16_bf16 v[96:111], v[224:227], v[144:147], v[96:111]
	ds_read_b128 v[220:223], v187 offset:6720
	v_cvt_pk_bf16_f32 v124, v56, v57
	v_cvt_pk_bf16_f32 v125, v58, v59
	v_cvt_pk_bf16_f32 v126, v60, v61
	v_cvt_pk_bf16_f32 v127, v62, v63
	v_add_f32_e32 v51, v67, v51
	v_add_f32_e32 v243, v243, v51
	s_waitcnt lgkmcnt(6)
	v_mfma_f32_32x32x16_bf16 v[96:111], v[128:131], v[148:151], v[96:111]
	ds_read_b128 v[224:227], v209 offset:58464
	v_add_f32_e32 v52, v68, v52
	v_add_f32_e32 v240, v240, v52
	v_add_f32_e32 v53, v69, v53
	v_add_f32_e32 v241, v241, v53
	v_add_f32_e32 v54, v70, v54
	v_add_f32_e32 v238, v238, v54
	s_waitcnt lgkmcnt(6)
	v_mfma_f32_32x32x16_bf16 v[96:111], v[132:135], v[152:155], v[96:111]
	ds_read_b128 v[128:131], v209 offset:63072
	v_add_f32_e32 v55, v71, v55
	v_add_f32_e32 v239, v239, v55
	v_add_f32_e32 v56, v72, v56
	v_add_f32_e32 v236, v236, v56
	v_add_f32_e32 v57, v73, v57
	v_add_f32_e32 v237, v237, v57
	s_waitcnt lgkmcnt(6)
	v_mfma_f32_32x32x16_bf16 v[96:111], v[136:139], v[156:159], v[96:111]
	ds_read_b128 v[132:135], v187 offset:6752
	v_add_f32_e32 v58, v74, v58
	v_add_f32_e32 v234, v234, v58
	v_add_f32_e32 v59, v75, v59
	v_add_f32_e32 v235, v235, v59
	v_add_f32_e32 v60, v76, v60
	v_add_f32_e32 v232, v232, v60
	s_waitcnt lgkmcnt(6)
	v_mfma_f32_32x32x16_bf16 v[96:111], v[140:143], v[160:163], v[96:111]
	ds_read_b128 v[136:139], v187 offset:6784
	v_add_f32_e32 v61, v77, v61
	v_add_f32_e32 v233, v233, v61
	v_add_f32_e32 v62, v78, v62
	v_add_f32_e32 v230, v230, v62
	s_waitcnt lgkmcnt(6)
	v_mfma_f32_32x32x16_bf16 v[80:95], v[188:191], v[164:167], v[0:15]
	ds_read_b128 v[140:143], v187 offset:6816
	v_add_f32_e32 v63, v79, v63
	v_add_f32_e32 v231, v231, v63
	s_waitcnt lgkmcnt(6)
	v_mfma_f32_32x32x16_bf16 v[80:95], v[168:171], v[144:147], v[80:95]
	ds_read_b128 v[188:191], v209 offset:13312
	v_exp_f32_e32 v96, v96
	v_exp_f32_e32 v97, v97
	v_exp_f32_e32 v98, v98
	s_waitcnt lgkmcnt(6)
	v_mfma_f32_32x32x16_bf16 v[80:95], v[220:223], v[148:151], v[80:95]
	ds_read_b128 v[168:171], v209 offset:17920
	v_exp_f32_e32 v99, v99
	v_exp_f32_e32 v100, v100
	v_exp_f32_e32 v101, v101
	s_waitcnt lgkmcnt(6)
	v_mfma_f32_32x32x16_bf16 v[16:31], v[224:227], v[124:127], v[16:31]
	ds_read_b128 v[220:223], v209 offset:13344
	v_exp_f32_e32 v102, v102
	v_exp_f32_e32 v103, v103
	v_cvt_pk_bf16_f32 v112, v96, v97
	v_cvt_pk_bf16_f32 v113, v98, v99
	s_waitcnt lgkmcnt(6)
	v_mfma_f32_32x32x16_bf16 v[32:47], v[128:131], v[124:127], v[32:47]
	ds_read_b128 v[224:227], v209 offset:17952
	v_cvt_pk_bf16_f32 v114, v100, v101
	v_cvt_pk_bf16_f32 v115, v102, v103
	v_exp_f32_e32 v104, v104
	v_exp_f32_e32 v105, v105
	s_waitcnt lgkmcnt(6)
	v_mfma_f32_32x32x16_bf16 v[80:95], v[132:135], v[152:155], v[80:95]
	v_exp_f32_e32 v106, v106
	v_exp_f32_e32 v107, v107
	v_exp_f32_e32 v108, v108
	s_waitcnt lgkmcnt(5)
	v_mfma_f32_32x32x16_bf16 v[80:95], v[136:139], v[156:159], v[80:95]
	v_exp_f32_e32 v109, v109
	v_exp_f32_e32 v110, v110
	v_exp_f32_e32 v111, v111
	s_waitcnt lgkmcnt(4)
	v_mfma_f32_32x32x16_bf16 v[80:95], v[140:143], v[160:163], v[80:95]
	v_cvt_pk_bf16_f32 v116, v104, v105
	v_cvt_pk_bf16_f32 v117, v106, v107
	v_cvt_pk_bf16_f32 v118, v108, v109
	v_cvt_pk_bf16_f32 v119, v110, v111
	s_waitcnt lgkmcnt(4)
	s_barrier
	ds_read_b128 v[128:131], v209 offset:13376
	ds_read_b128 v[132:135], v209 offset:17984
	ds_read_b128 v[136:139], v187 offset:22528
	s_waitcnt lgkmcnt(6)
	v_mfma_f32_32x32x16_bf16 v[16:31], v[188:191], v[112:115], v[16:31]
	ds_read_b128 v[140:143], v187 offset:22560
	s_waitcnt vmcnt(0)
	ds_write_b128 v211, v[176:179] offset:45056
	s_and_saveexec_b64 s[42:43], s[36:37]
	s_cbranch_execz .Lattn_fx_w6
	ds_write_b128 v186, v[172:175] offset:45056
.Lattn_fx_w6:
	s_or_b64 exec, exec, s[42:43]
	ds_write_b128 v208, v[180:183] offset:58368
	v_exp_f32_e32 v80, v80
	v_exp_f32_e32 v81, v81
	v_exp_f32_e32 v82, v82
	s_waitcnt lgkmcnt(8)
	v_mfma_f32_32x32x16_bf16 v[32:47], v[168:171], v[112:115], v[32:47]
	ds_read_b128 v[188:191], v187 offset:22592
	global_load_dwordx4 v[176:179], v212, s[6:7]
	s_and_saveexec_b64 s[42:43], s[36:37]
	s_cbranch_execz .Lattn_fx_g7
	global_load_dwordx4 v[172:175], v214, s[6:7]
.Lattn_fx_g7:
	s_or_b64 exec, exec, s[42:43]
	global_load_dwordx4 v[180:183], v204, s[40:41]
	s_add_u32 s6, s6, 0x18000
	s_addc_u32 s7, s7, 0
	s_add_u32 s40, s40, 0x80
	s_addc_u32 s41, s41, 0
	v_exp_f32_e32 v83, v83
	v_exp_f32_e32 v84, v84
	v_exp_f32_e32 v85, v85
	s_waitcnt lgkmcnt(8)
	v_mfma_f32_32x32x16_bf16 v[16:31], v[220:223], v[116:119], v[16:31]
	ds_read_b128 v[168:171], v187 offset:22624
	v_exp_f32_e32 v86, v86
	v_exp_f32_e32 v87, v87
	v_cvt_pk_bf16_f32 v120, v80, v81
	v_cvt_pk_bf16_f32 v121, v82, v83
	s_waitcnt lgkmcnt(8)
	v_mfma_f32_32x32x16_bf16 v[32:47], v[224:227], v[116:119], v[32:47]
	ds_read_b128 v[220:223], v187 offset:22656
	v_cvt_pk_bf16_f32 v122, v84, v85
	v_cvt_pk_bf16_f32 v123, v86, v87
	v_exp_f32_e32 v88, v88
	v_exp_f32_e32 v89, v89
	s_waitcnt lgkmcnt(8)
	v_mfma_f32_32x32x16_bf16 v[16:31], v[128:131], v[120:123], v[16:31]
	ds_read_b128 v[224:227], v187 offset:22688
	v_exp_f32_e32 v90, v90
	v_exp_f32_e32 v91, v91
	v_add_f32_e32 v80, v96, v80
	v_add_f32_e32 v244, v244, v80
	s_waitcnt lgkmcnt(8)
	v_mfma_f32_32x32x16_bf16 v[32:47], v[132:135], v[120:123], v[32:47]
	ds_read_b128 v[128:131], v187 offset:29184
	v_exp_f32_e32 v92, v92
	v_exp_f32_e32 v93, v93
	v_add_f32_e32 v81, v97, v81
	v_add_f32_e32 v245, v245, v81
	s_waitcnt lgkmcnt(8)
	v_mfma_f32_32x32x16_bf16 v[64:79], v[136:139], v[164:167], v[0:15]
	ds_read_b128 v[132:135], v187 offset:29216
	v_exp_f32_e32 v94, v94
	v_exp_f32_e32 v95, v95
	v_add_f32_e32 v82, v98, v82
	v_add_f32_e32 v242, v242, v82
	s_waitcnt lgkmcnt(8)
	v_mfma_f32_32x32x16_bf16 v[64:79], v[140:143], v[144:147], v[64:79]
	ds_read_b128 v[136:139], v187 offset:29248
	v_cvt_pk_bf16_f32 v124, v88, v89
	v_cvt_pk_bf16_f32 v125, v90, v91
	v_cvt_pk_bf16_f32 v126, v92, v93
	v_cvt_pk_bf16_f32 v127, v94, v95
	v_add_f32_e32 v83, v99, v83
	v_add_f32_e32 v243, v243, v83
	s_waitcnt lgkmcnt(6)
	v_mfma_f32_32x32x16_bf16 v[64:79], v[188:191], v[148:151], v[64:79]
	ds_read_b128 v[140:143], v209 offset:13408
	v_add_f32_e32 v84, v100, v84
	v_add_f32_e32 v240, v240, v84
	v_add_f32_e32 v85, v101, v85
	v_add_f32_e32 v241, v241, v85
	v_add_f32_e32 v86, v102, v86
	v_add_f32_e32 v238, v238, v86
	s_waitcnt lgkmcnt(6)
	v_mfma_f32_32x32x16_bf16 v[64:79], v[168:171], v[152:155], v[64:79]
	ds_read_b128 v[188:191], v209 offset:18016
	v_add_f32_e32 v87, v103, v87
	v_add_f32_e32 v239, v239, v87
	v_add_f32_e32 v88, v104, v88
	v_add_f32_e32 v236, v236, v88
	v_add_f32_e32 v89, v105, v89
	v_add_f32_e32 v237, v237, v89
	s_waitcnt lgkmcnt(6)
	v_mfma_f32_32x32x16_bf16 v[64:79], v[220:223], v[156:159], v[64:79]
	ds_read_b128 v[168:171], v187 offset:29280
	v_add_f32_e32 v90, v106, v90
	v_add_f32_e32 v234, v234, v90
	v_add_f32_e32 v91, v107, v91
	v_add_f32_e32 v235, v235, v91
	v_add_f32_e32 v92, v108, v92
	v_add_f32_e32 v232, v232, v92
	s_waitcnt lgkmcnt(6)
	v_mfma_f32_32x32x16_bf16 v[64:79], v[224:227], v[160:163], v[64:79]
	ds_read_b128 v[220:223], v187 offset:29312
	v_add_f32_e32 v93, v109, v93
	v_add_f32_e32 v233, v233, v93
	v_add_f32_e32 v94, v110, v94
	v_add_f32_e32 v230, v230, v94
	s_waitcnt lgkmcnt(6)
	v_mfma_f32_32x32x16_bf16 v[48:63], v[128:131], v[164:167], v[0:15]
	ds_read_b128 v[224:227], v187 offset:29344
	v_add_f32_e32 v95, v111, v95
	v_add_f32_e32 v231, v231, v95
	s_waitcnt lgkmcnt(6)
	v_mfma_f32_32x32x16_bf16 v[48:63], v[132:135], v[144:147], v[48:63]
	ds_read_b128 v[128:131], v209 offset:35840
	v_exp_f32_e32 v64, v64
	v_exp_f32_e32 v65, v65
	v_exp_f32_e32 v66, v66
	s_waitcnt lgkmcnt(6)
	v_mfma_f32_32x32x16_bf16 v[48:63], v[136:139], v[148:151], v[48:63]
	ds_read_b128 v[132:135], v209 offset:40448
	v_exp_f32_e32 v67, v67
	v_exp_f32_e32 v68, v68
	v_exp_f32_e32 v69, v69
	s_waitcnt lgkmcnt(6)
	v_mfma_f32_32x32x16_bf16 v[16:31], v[140:143], v[124:127], v[16:31]
	ds_read_b128 v[136:139], v209 offset:35872
	v_exp_f32_e32 v70, v70
	v_exp_f32_e32 v71, v71
	v_cvt_pk_bf16_f32 v112, v64, v65
	v_cvt_pk_bf16_f32 v113, v66, v67
	s_waitcnt lgkmcnt(6)
	v_mfma_f32_32x32x16_bf16 v[32:47], v[188:191], v[124:127], v[32:47]
	ds_read_b128 v[140:143], v209 offset:40480
	v_cvt_pk_bf16_f32 v114, v68, v69
	v_cvt_pk_bf16_f32 v115, v70, v71
	v_exp_f32_e32 v72, v72
	v_exp_f32_e32 v73, v73
	s_waitcnt lgkmcnt(6)
	v_mfma_f32_32x32x16_bf16 v[48:63], v[168:171], v[152:155], v[48:63]
	v_exp_f32_e32 v74, v74
	v_exp_f32_e32 v75, v75
	v_exp_f32_e32 v76, v76
	s_waitcnt lgkmcnt(5)
	v_mfma_f32_32x32x16_bf16 v[48:63], v[220:223], v[156:159], v[48:63]
	v_exp_f32_e32 v77, v77
	v_exp_f32_e32 v78, v78
	v_exp_f32_e32 v79, v79
	s_waitcnt lgkmcnt(4)
	v_mfma_f32_32x32x16_bf16 v[48:63], v[224:227], v[160:163], v[48:63]
	v_cvt_pk_bf16_f32 v116, v72, v73
	v_cvt_pk_bf16_f32 v117, v74, v75
	v_cvt_pk_bf16_f32 v118, v76, v77
	v_cvt_pk_bf16_f32 v119, v78, v79
	s_waitcnt lgkmcnt(4)
	s_barrier
	ds_read_b128 v[188:191], v209 offset:35904
	ds_read_b128 v[168:171], v209 offset:40512
	ds_read_b128 v[220:223], v187 offset:45056
	s_waitcnt lgkmcnt(6)
	v_mfma_f32_32x32x16_bf16 v[16:31], v[128:131], v[112:115], v[16:31]
	ds_read_b128 v[224:227], v187 offset:45088
	s_waitcnt vmcnt(0)
	ds_write_b128 v211, v[176:179] offset:0
	s_and_saveexec_b64 s[42:43], s[36:37]
	s_cbranch_execz .Lattn_fx_w8
	ds_write_b128 v186, v[172:175] offset:0
.Lattn_fx_w8:
	s_or_b64 exec, exec, s[42:43]
	ds_write_b128 v208, v[180:183] offset:13312
	v_exp_f32_e32 v48, v48
	v_exp_f32_e32 v49, v49
	v_exp_f32_e32 v50, v50
	s_waitcnt lgkmcnt(8)
	v_mfma_f32_32x32x16_bf16 v[32:47], v[132:135], v[112:115], v[32:47]
	ds_read_b128 v[128:131], v187 offset:45120
	global_load_dwordx4 v[176:179], v212, s[6:7]
	s_and_saveexec_b64 s[42:43], s[36:37]
	s_cbranch_execz .Lattn_fx_g9
	global_load_dwordx4 v[172:175], v214, s[6:7]
.Lattn_fx_g9:
	s_or_b64 exec, exec, s[42:43]
	global_load_dwordx4 v[180:183], v204, s[40:41]
	s_add_u32 s6, s6, 0x18000
	s_addc_u32 s7, s7, 0
	s_add_u32 s40, s40, 0x80
	s_addc_u32 s41, s41, 0
	v_exp_f32_e32 v51, v51
	v_exp_f32_e32 v52, v52
	v_exp_f32_e32 v53, v53
	s_waitcnt lgkmcnt(8)
	v_mfma_f32_32x32x16_bf16 v[16:31], v[136:139], v[116:119], v[16:31]
	ds_read_b128 v[132:135], v187 offset:45152
	v_exp_f32_e32 v54, v54
	v_exp_f32_e32 v55, v55
	v_cvt_pk_bf16_f32 v120, v48, v49
	v_cvt_pk_bf16_f32 v121, v50, v51
	s_waitcnt lgkmcnt(8)
	v_mfma_f32_32x32x16_bf16 v[32:47], v[140:143], v[116:119], v[32:47]
	ds_read_b128 v[136:139], v187 offset:45184
	v_cvt_pk_bf16_f32 v122, v52, v53
	v_cvt_pk_bf16_f32 v123, v54, v55
	v_exp_f32_e32 v56, v56
	v_exp_f32_e32 v57, v57
	s_waitcnt lgkmcnt(8)
	v_mfma_f32_32x32x16_bf16 v[16:31], v[188:191], v[120:123], v[16:31]
	ds_read_b128 v[140:143], v187 offset:45216
	v_exp_f32_e32 v58, v58
	v_exp_f32_e32 v59, v59
	v_add_f32_e32 v48, v64, v48
	v_add_f32_e32 v244, v244, v48
	s_waitcnt lgkmcnt(8)
	v_mfma_f32_32x32x16_bf16 v[32:47], v[168:171], v[120:123], v[32:47]
	ds_read_b128 v[188:191], v187 offset:51712
	v_exp_f32_e32 v60, v60
	v_exp_f32_e32 v61, v61
	v_add_f32_e32 v49, v65, v49
	v_add_f32_e32 v245, v245, v49
	s_waitcnt lgkmcnt(8)
	v_mfma_f32_32x32x16_bf16 v[96:111], v[220:223], v[164:167], v[0:15]
	ds_read_b128 v[168:171], v187 offset:51744
	v_exp_f32_e32 v62, v62
	v_exp_f32_e32 v63, v63
	v_add_f32_e32 v50, v66, v50
	v_add_f32_e32 v242, v242, v50
	s_waitcnt lgkmcnt(8)
	v_mfma_f32_32x32x16_bf16 v[96:111], v[224:227], v[144:147], v[96:111]
	ds_read_b128 v[220:223], v187 offset:51776
	v_cvt_pk_bf16_f32 v124, v56, v57
	v_cvt_pk_bf16_f32 v125, v58, v59
	v_cvt_pk_bf16_f32 v126, v60, v61
	v_cvt_pk_bf16_f32 v127, v62, v63
	v_add_f32_e32 v51, v67, v51
	v_add_f32_e32 v243, v243, v51
	s_waitcnt lgkmcnt(6)
	v_mfma_f32_32x32x16_bf16 v[96:111], v[128:131], v[148:151], v[96:111]
	ds_read_b128 v[224:227], v209 offset:35936
	v_add_f32_e32 v52, v68, v52
	v_add_f32_e32 v240, v240, v52
	v_add_f32_e32 v53, v69, v53
	v_add_f32_e32 v241, v241, v53
	v_add_f32_e32 v54, v70, v54
	v_add_f32_e32 v238, v238, v54
	s_waitcnt lgkmcnt(6)
	v_mfma_f32_32x32x16_bf16 v[96:111], v[132:135], v[152:155], v[96:111]
	ds_read_b128 v[128:131], v209 offset:40544
	v_add_f32_e32 v55, v71, v55
	v_add_f32_e32 v239, v239, v55
	v_add_f32_e32 v56, v72, v56
	v_add_f32_e32 v236, v236, v56
	v_add_f32_e32 v57, v73, v57
	v_add_f32_e32 v237, v237, v57
	s_waitcnt lgkmcnt(6)
	v_mfma_f32_32x32x16_bf16 v[96:111], v[136:139], v[156:159], v[96:111]
	ds_read_b128 v[132:135], v187 offset:51808
	v_add_f32_e32 v58, v74, v58
	v_add_f32_e32 v234, v234, v58
	v_add_f32_e32 v59, v75, v59
	v_add_f32_e32 v235, v235, v59
	v_add_f32_e32 v60, v76, v60
	v_add_f32_e32 v232, v232, v60
	s_waitcnt lgkmcnt(6)
	v_mfma_f32_32x32x16_bf16 v[96:111], v[140:143], v[160:163], v[96:111]
	ds_read_b128 v[136:139], v187 offset:51840
	v_add_f32_e32 v61, v77, v61
	v_add_f32_e32 v233, v233, v61
	v_add_f32_e32 v62, v78, v62
	v_add_f32_e32 v230, v230, v62
	s_waitcnt lgkmcnt(6)
	v_mfma_f32_32x32x16_bf16 v[80:95], v[188:191], v[164:167], v[0:15]
	ds_read_b128 v[140:143], v187 offset:51872
	v_add_f32_e32 v63, v79, v63
	v_add_f32_e32 v231, v231, v63
	s_waitcnt lgkmcnt(6)
	v_mfma_f32_32x32x16_bf16 v[80:95], v[168:171], v[144:147], v[80:95]
	ds_read_b128 v[188:191], v209 offset:58368
	v_exp_f32_e32 v96, v96
	v_exp_f32_e32 v97, v97
	v_exp_f32_e32 v98, v98
	s_waitcnt lgkmcnt(6)
	v_mfma_f32_32x32x16_bf16 v[80:95], v[220:223], v[148:151], v[80:95]
	ds_read_b128 v[168:171], v209 offset:62976
	v_exp_f32_e32 v99, v99
	v_exp_f32_e32 v100, v100
	v_exp_f32_e32 v101, v101
	s_waitcnt lgkmcnt(6)
	v_mfma_f32_32x32x16_bf16 v[16:31], v[224:227], v[124:127], v[16:31]
	ds_read_b128 v[220:223], v209 offset:58400
	v_exp_f32_e32 v102, v102
	v_exp_f32_e32 v103, v103
	v_cvt_pk_bf16_f32 v112, v96, v97
	v_cvt_pk_bf16_f32 v113, v98, v99
	s_waitcnt lgkmcnt(6)
	v_mfma_f32_32x32x16_bf16 v[32:47], v[128:131], v[124:127], v[32:47]
	ds_read_b128 v[224:227], v209 offset:63008
	v_cvt_pk_bf16_f32 v114, v100, v101
	v_cvt_pk_bf16_f32 v115, v102, v103
	v_exp_f32_e32 v104, v104
	v_exp_f32_e32 v105, v105
	s_waitcnt lgkmcnt(6)
	v_mfma_f32_32x32x16_bf16 v[80:95], v[132:135], v[152:155], v[80:95]
	v_exp_f32_e32 v106, v106
	v_exp_f32_e32 v107, v107
	v_exp_f32_e32 v108, v108
	s_waitcnt lgkmcnt(5)
	v_mfma_f32_32x32x16_bf16 v[80:95], v[136:139], v[156:159], v[80:95]
	v_exp_f32_e32 v109, v109
	v_exp_f32_e32 v110, v110
	v_exp_f32_e32 v111, v111
	s_waitcnt lgkmcnt(4)
	v_mfma_f32_32x32x16_bf16 v[80:95], v[140:143], v[160:163], v[80:95]
	v_cvt_pk_bf16_f32 v116, v104, v105
	v_cvt_pk_bf16_f32 v117, v106, v107
	v_cvt_pk_bf16_f32 v118, v108, v109
	v_cvt_pk_bf16_f32 v119, v110, v111
	s_waitcnt lgkmcnt(4)
	s_barrier
	ds_read_b128 v[128:131], v209 offset:58432
	ds_read_b128 v[132:135], v209 offset:63040
	ds_read_b128 v[136:139], v187 offset:0
	s_waitcnt lgkmcnt(6)
	v_mfma_f32_32x32x16_bf16 v[16:31], v[188:191], v[112:115], v[16:31]
	ds_read_b128 v[140:143], v187 offset:32
	s_waitcnt vmcnt(0)
	ds_write_b128 v211, v[176:179] offset:22528
	s_and_saveexec_b64 s[42:43], s[36:37]
	s_cbranch_execz .Lattn_fx_w10
	ds_write_b128 v186, v[172:175] offset:22528
.Lattn_fx_w10:
	s_or_b64 exec, exec, s[42:43]
	ds_write_b128 v208, v[180:183] offset:35840
	v_exp_f32_e32 v80, v80
	v_exp_f32_e32 v81, v81
	v_exp_f32_e32 v82, v82
	s_waitcnt lgkmcnt(8)
	v_mfma_f32_32x32x16_bf16 v[32:47], v[168:171], v[112:115], v[32:47]
	ds_read_b128 v[188:191], v187 offset:64
	s_cmp_eq_u32 s14, 20
	s_cbranch_scc1 .Lattn_fx_skipld
	global_load_dwordx4 v[176:179], v212, s[6:7]
	s_and_saveexec_b64 s[42:43], s[36:37]
	s_cbranch_execz .Lattn_fx_g11
	global_load_dwordx4 v[172:175], v214, s[6:7]

.Lattn_fx_skipld:
	v_exp_f32_e32 v83, v83
	v_exp_f32_e32 v84, v84
	v_exp_f32_e32 v85, v85
	s_waitcnt lgkmcnt(8)
	v_mfma_f32_32x32x16_bf16 v[16:31], v[220:223], v[116:119], v[16:31]
	ds_read_b128 v[168:171], v187 offset:96
	v_exp_f32_e32 v86, v86
	v_exp_f32_e32 v87, v87
	v_cvt_pk_bf16_f32 v120, v80, v81
	v_cvt_pk_bf16_f32 v121, v82, v83
	s_waitcnt lgkmcnt(8)
	v_mfma_f32_32x32x16_bf16 v[32:47], v[224:227], v[116:119], v[32:47]
	ds_read_b128 v[220:223], v187 offset:128
	v_cvt_pk_bf16_f32 v122, v84, v85
	v_cvt_pk_bf16_f32 v123, v86, v87
	v_exp_f32_e32 v88, v88
	v_exp_f32_e32 v89, v89
	s_waitcnt lgkmcnt(8)
	v_mfma_f32_32x32x16_bf16 v[16:31], v[128:131], v[120:123], v[16:31]
	ds_read_b128 v[224:227], v187 offset:160
	v_exp_f32_e32 v90, v90
	v_exp_f32_e32 v91, v91
	v_add_f32_e32 v80, v96, v80
	v_add_f32_e32 v244, v244, v80
	s_waitcnt lgkmcnt(8)
	v_mfma_f32_32x32x16_bf16 v[32:47], v[132:135], v[120:123], v[32:47]
	ds_read_b128 v[128:131], v187 offset:6656
	v_exp_f32_e32 v92, v92
	v_exp_f32_e32 v93, v93
	v_add_f32_e32 v81, v97, v81
	v_add_f32_e32 v245, v245, v81
	s_waitcnt lgkmcnt(8)
	v_mfma_f32_32x32x16_bf16 v[64:79], v[136:139], v[164:167], v[0:15]
	ds_read_b128 v[132:135], v187 offset:6688
	v_exp_f32_e32 v94, v94
	v_exp_f32_e32 v95, v95
	v_add_f32_e32 v82, v98, v82
	v_add_f32_e32 v242, v242, v82
	s_waitcnt lgkmcnt(8)
	v_mfma_f32_32x32x16_bf16 v[64:79], v[140:143], v[144:147], v[64:79]
	ds_read_b128 v[136:139], v187 offset:6720
	v_cvt_pk_bf16_f32 v124, v88, v89
	v_cvt_pk_bf16_f32 v125, v90, v91
	v_cvt_pk_bf16_f32 v126, v92, v93
	v_cvt_pk_bf16_f32 v127, v94, v95
	v_add_f32_e32 v83, v99, v83
	v_add_f32_e32 v243, v243, v83
	s_waitcnt lgkmcnt(6)
	v_mfma_f32_32x32x16_bf16 v[64:79], v[188:191], v[148:151], v[64:79]
	ds_read_b128 v[140:143], v209 offset:58464
	v_add_f32_e32 v84, v100, v84
	v_add_f32_e32 v240, v240, v84
	v_add_f32_e32 v85, v101, v85
	v_add_f32_e32 v241, v241, v85
	v_add_f32_e32 v86, v102, v86
	v_add_f32_e32 v238, v238, v86
	s_waitcnt lgkmcnt(6)
	v_mfma_f32_32x32x16_bf16 v[64:79], v[168:171], v[152:155], v[64:79]
	ds_read_b128 v[188:191], v209 offset:63072
	v_add_f32_e32 v87, v103, v87
	v_add_f32_e32 v239, v239, v87
	v_add_f32_e32 v88, v104, v88
	v_add_f32_e32 v236, v236, v88
	v_add_f32_e32 v89, v105, v89
	v_add_f32_e32 v237, v237, v89
	s_waitcnt lgkmcnt(6)
	v_mfma_f32_32x32x16_bf16 v[64:79], v[220:223], v[156:159], v[64:79]
	ds_read_b128 v[168:171], v187 offset:6752
	v_add_f32_e32 v90, v106, v90
	v_add_f32_e32 v234, v234, v90
	v_add_f32_e32 v91, v107, v91
	v_add_f32_e32 v235, v235, v91
	v_add_f32_e32 v92, v108, v92
	v_add_f32_e32 v232, v232, v92
	s_waitcnt lgkmcnt(6)
	v_mfma_f32_32x32x16_bf16 v[64:79], v[224:227], v[160:163], v[64:79]
	ds_read_b128 v[220:223], v187 offset:6784
	v_add_f32_e32 v93, v109, v93
	v_add_f32_e32 v233, v233, v93
	v_add_f32_e32 v94, v110, v94
	v_add_f32_e32 v230, v230, v94
	s_waitcnt lgkmcnt(6)
	v_mfma_f32_32x32x16_bf16 v[48:63], v[128:131], v[164:167], v[0:15]
	ds_read_b128 v[224:227], v187 offset:6816
	v_add_f32_e32 v95, v111, v95
	v_add_f32_e32 v231, v231, v95
	s_waitcnt lgkmcnt(6)
	v_mfma_f32_32x32x16_bf16 v[48:63], v[132:135], v[144:147], v[48:63]
	ds_read_b128 v[128:131], v209 offset:13312
	v_exp_f32_e32 v64, v64
	v_exp_f32_e32 v65, v65
	v_exp_f32_e32 v66, v66
	s_waitcnt lgkmcnt(6)
	v_mfma_f32_32x32x16_bf16 v[48:63], v[136:139], v[148:151], v[48:63]
	ds_read_b128 v[132:135], v209 offset:17920
	v_exp_f32_e32 v67, v67
	v_exp_f32_e32 v68, v68
	v_exp_f32_e32 v69, v69
	s_waitcnt lgkmcnt(6)
	v_mfma_f32_32x32x16_bf16 v[16:31], v[140:143], v[124:127], v[16:31]
	ds_read_b128 v[136:139], v209 offset:13344
	v_exp_f32_e32 v70, v70
	v_exp_f32_e32 v71, v71
	v_cvt_pk_bf16_f32 v112, v64, v65
	v_cvt_pk_bf16_f32 v113, v66, v67
	s_waitcnt lgkmcnt(6)
	v_mfma_f32_32x32x16_bf16 v[32:47], v[188:191], v[124:127], v[32:47]
	ds_read_b128 v[140:143], v209 offset:17952
	v_cvt_pk_bf16_f32 v114, v68, v69
	v_cvt_pk_bf16_f32 v115, v70, v71
	v_exp_f32_e32 v72, v72
	v_exp_f32_e32 v73, v73
	s_waitcnt lgkmcnt(6)
	v_mfma_f32_32x32x16_bf16 v[48:63], v[168:171], v[152:155], v[48:63]
	v_exp_f32_e32 v74, v74
	v_exp_f32_e32 v75, v75
	v_exp_f32_e32 v76, v76
	s_waitcnt lgkmcnt(5)
	v_mfma_f32_32x32x16_bf16 v[48:63], v[220:223], v[156:159], v[48:63]
	v_exp_f32_e32 v77, v77
	v_exp_f32_e32 v78, v78
	v_exp_f32_e32 v79, v79
	s_waitcnt lgkmcnt(4)
	v_mfma_f32_32x32x16_bf16 v[48:63], v[224:227], v[160:163], v[48:63]
	v_cvt_pk_bf16_f32 v116, v72, v73
	v_cvt_pk_bf16_f32 v117, v74, v75
	v_cvt_pk_bf16_f32 v118, v76, v77
	v_cvt_pk_bf16_f32 v119, v78, v79
	s_waitcnt lgkmcnt(4)
	s_barrier
	s_add_i32 s14, s14, 1
	s_cmp_lt_u32 s14, 21
	s_cbranch_scc1 .Lattn_fx_loop
	ds_read_b128 v[188:191], v209 offset:13376
	ds_read_b128 v[168:171], v209 offset:17984
	ds_read_b128 v[220:223], v187 offset:22528
	s_waitcnt lgkmcnt(6)
	v_mfma_f32_32x32x16_bf16 v[16:31], v[128:131], v[112:115], v[16:31]
	ds_read_b128 v[224:227], v187 offset:22560
	s_nop 7
	v_exp_f32_e32 v48, v48
	v_exp_f32_e32 v49, v49
	v_exp_f32_e32 v50, v50
	s_waitcnt lgkmcnt(6)
	v_mfma_f32_32x32x16_bf16 v[32:47], v[132:135], v[112:115], v[32:47]
	ds_read_b128 v[128:131], v187 offset:22592
	v_exp_f32_e32 v51, v51
	v_exp_f32_e32 v52, v52
	v_exp_f32_e32 v53, v53
	s_waitcnt lgkmcnt(6)
	v_mfma_f32_32x32x16_bf16 v[16:31], v[136:139], v[116:119], v[16:31]
	ds_read_b128 v[132:135], v187 offset:22624
	v_exp_f32_e32 v54, v54
	v_exp_f32_e32 v55, v55
	v_cvt_pk_bf16_f32 v120, v48, v49
	v_cvt_pk_bf16_f32 v121, v50, v51
	s_waitcnt lgkmcnt(6)
	v_mfma_f32_32x32x16_bf16 v[32:47], v[140:143], v[116:119], v[32:47]
	ds_read_b128 v[136:139], v187 offset:22656
	v_cvt_pk_bf16_f32 v122, v52, v53
	v_cvt_pk_bf16_f32 v123, v54, v55
	v_exp_f32_e32 v56, v56
	v_exp_f32_e32 v57, v57
	s_waitcnt lgkmcnt(6)
	v_mfma_f32_32x32x16_bf16 v[16:31], v[188:191], v[120:123], v[16:31]
	ds_read_b128 v[140:143], v187 offset:22688
	v_exp_f32_e32 v58, v58
	v_exp_f32_e32 v59, v59
	v_add_f32_e32 v48, v64, v48
	v_add_f32_e32 v244, v244, v48
	s_waitcnt lgkmcnt(6)
	v_mfma_f32_32x32x16_bf16 v[32:47], v[168:171], v[120:123], v[32:47]
	ds_read_b128 v[188:191], v187 offset:29184
	v_exp_f32_e32 v60, v60
	v_exp_f32_e32 v61, v61
	v_add_f32_e32 v49, v65, v49
	v_add_f32_e32 v245, v245, v49
	s_waitcnt lgkmcnt(6)
	v_mfma_f32_32x32x16_bf16 v[96:111], v[220:223], v[164:167], v[0:15]
	ds_read_b128 v[168:171], v187 offset:29216
	v_exp_f32_e32 v62, v62
	v_exp_f32_e32 v63, v63
	v_add_f32_e32 v50, v66, v50
	v_add_f32_e32 v242, v242, v50
	s_waitcnt lgkmcnt(6)
	v_mfma_f32_32x32x16_bf16 v[96:111], v[224:227], v[144:147], v[96:111]
	ds_read_b128 v[220:223], v187 offset:29248
	v_cvt_pk_bf16_f32 v124, v56, v57
	v_cvt_pk_bf16_f32 v125, v58, v59
	v_cvt_pk_bf16_f32 v126, v60, v61
	v_cvt_pk_bf16_f32 v127, v62, v63
	v_add_f32_e32 v51, v67, v51
	v_add_f32_e32 v243, v243, v51
	s_waitcnt lgkmcnt(6)
	v_mfma_f32_32x32x16_bf16 v[96:111], v[128:131], v[148:151], v[96:111]
	ds_read_b128 v[224:227], v209 offset:13408
	v_add_f32_e32 v52, v68, v52
	v_add_f32_e32 v240, v240, v52
	v_add_f32_e32 v53, v69, v53
	v_add_f32_e32 v241, v241, v53
	v_add_f32_e32 v54, v70, v54
	v_add_f32_e32 v238, v238, v54
	s_waitcnt lgkmcnt(6)
	v_mfma_f32_32x32x16_bf16 v[96:111], v[132:135], v[152:155], v[96:111]
	ds_read_b128 v[128:131], v209 offset:18016
	v_add_f32_e32 v55, v71, v55
	v_add_f32_e32 v239, v239, v55
	v_add_f32_e32 v56, v72, v56
	v_add_f32_e32 v236, v236, v56
	v_add_f32_e32 v57, v73, v57
	v_add_f32_e32 v237, v237, v57
	s_waitcnt lgkmcnt(6)
	v_mfma_f32_32x32x16_bf16 v[96:111], v[136:139], v[156:159], v[96:111]
	ds_read_b128 v[132:135], v187 offset:29280
	v_add_f32_e32 v58, v74, v58
	v_add_f32_e32 v234, v234, v58
	v_add_f32_e32 v59, v75, v59
	v_add_f32_e32 v235, v235, v59
	v_add_f32_e32 v60, v76, v60
	v_add_f32_e32 v232, v232, v60
	s_waitcnt lgkmcnt(6)
	v_mfma_f32_32x32x16_bf16 v[96:111], v[140:143], v[160:163], v[96:111]
	ds_read_b128 v[136:139], v187 offset:29312
	v_add_f32_e32 v61, v77, v61
	v_add_f32_e32 v233, v233, v61
	v_add_f32_e32 v62, v78, v62
	v_add_f32_e32 v230, v230, v62
	s_waitcnt lgkmcnt(6)
	v_mfma_f32_32x32x16_bf16 v[80:95], v[188:191], v[164:167], v[0:15]
	ds_read_b128 v[140:143], v187 offset:29344
	v_add_f32_e32 v63, v79, v63
	v_add_f32_e32 v231, v231, v63
	s_waitcnt lgkmcnt(6)
	v_mfma_f32_32x32x16_bf16 v[80:95], v[168:171], v[144:147], v[80:95]
	ds_read_b128 v[188:191], v209 offset:35840
	v_exp_f32_e32 v96, v96
	v_exp_f32_e32 v97, v97
	v_exp_f32_e32 v98, v98
	s_waitcnt lgkmcnt(6)
	v_mfma_f32_32x32x16_bf16 v[80:95], v[220:223], v[148:151], v[80:95]
	ds_read_b128 v[168:171], v209 offset:40448
	v_exp_f32_e32 v99, v99
	v_exp_f32_e32 v100, v100
	v_exp_f32_e32 v101, v101
	s_waitcnt lgkmcnt(6)
	v_mfma_f32_32x32x16_bf16 v[16:31], v[224:227], v[124:127], v[16:31]
	ds_read_b128 v[220:223], v209 offset:35872
	v_exp_f32_e32 v102, v102
	v_exp_f32_e32 v103, v103
	v_cvt_pk_bf16_f32 v112, v96, v97
	v_cvt_pk_bf16_f32 v113, v98, v99
	s_waitcnt lgkmcnt(6)
	v_mfma_f32_32x32x16_bf16 v[32:47], v[128:131], v[124:127], v[32:47]
	ds_read_b128 v[224:227], v209 offset:40480
	v_cvt_pk_bf16_f32 v114, v100, v101
	v_cvt_pk_bf16_f32 v115, v102, v103
	v_exp_f32_e32 v104, v104
	v_exp_f32_e32 v105, v105
	s_waitcnt lgkmcnt(6)
	v_mfma_f32_32x32x16_bf16 v[80:95], v[132:135], v[152:155], v[80:95]
	v_exp_f32_e32 v106, v106
	v_exp_f32_e32 v107, v107
	v_exp_f32_e32 v108, v108
	s_waitcnt lgkmcnt(5)
	v_mfma_f32_32x32x16_bf16 v[80:95], v[136:139], v[156:159], v[80:95]
	v_exp_f32_e32 v109, v109
	v_exp_f32_e32 v110, v110
	v_exp_f32_e32 v111, v111
	s_waitcnt lgkmcnt(4)
	v_mfma_f32_32x32x16_bf16 v[80:95], v[140:143], v[160:163], v[80:95]
	v_cvt_pk_bf16_f32 v116, v104, v105
	v_cvt_pk_bf16_f32 v117, v106, v107
	v_cvt_pk_bf16_f32 v118, v108, v109
	v_cvt_pk_bf16_f32 v119, v110, v111
	s_waitcnt lgkmcnt(4)
	s_barrier
	ds_read_b128 v[128:131], v209 offset:35904
	ds_read_b128 v[132:135], v209 offset:40512
	ds_read_b128 v[136:139], v209 offset:35936
	s_waitcnt lgkmcnt(6)
	v_mfma_f32_32x32x16_bf16 v[16:31], v[188:191], v[112:115], v[16:31]
	ds_read_b128 v[140:143], v209 offset:40544
	s_nop 7
	v_exp_f32_e32 v80, v80
	v_exp_f32_e32 v81, v81
	v_exp_f32_e32 v82, v82
	v_exp_f32_e32 v83, v83
	v_exp_f32_e32 v84, v84
	v_exp_f32_e32 v85, v85
	v_exp_f32_e32 v86, v86
	v_exp_f32_e32 v87, v87
	s_waitcnt lgkmcnt(6)
	v_mfma_f32_32x32x16_bf16 v[32:47], v[168:171], v[112:115], v[32:47]
	v_cvt_pk_bf16_f32 v120, v80, v81
	v_cvt_pk_bf16_f32 v121, v82, v83
	v_cvt_pk_bf16_f32 v122, v84, v85
	v_cvt_pk_bf16_f32 v123, v86, v87
	v_exp_f32_e32 v88, v88
	v_exp_f32_e32 v89, v89
	v_exp_f32_e32 v90, v90
	v_exp_f32_e32 v91, v91
	s_waitcnt lgkmcnt(5)
	v_mfma_f32_32x32x16_bf16 v[16:31], v[220:223], v[116:119], v[16:31]
	v_exp_f32_e32 v92, v92
	v_exp_f32_e32 v93, v93
	v_exp_f32_e32 v94, v94
	v_exp_f32_e32 v95, v95
	s_waitcnt lgkmcnt(4)
	v_mfma_f32_32x32x16_bf16 v[32:47], v[224:227], v[116:119], v[32:47]
	v_cvt_pk_bf16_f32 v124, v88, v89
	v_cvt_pk_bf16_f32 v125, v90, v91
	v_cvt_pk_bf16_f32 v126, v92, v93
	v_cvt_pk_bf16_f32 v127, v94, v95
	s_waitcnt lgkmcnt(3)
	v_mfma_f32_32x32x16_bf16 v[16:31], v[128:131], v[120:123], v[16:31]
	v_add_f32_e32 v80, v96, v80
	v_add_f32_e32 v244, v244, v80
	v_add_f32_e32 v81, v97, v81
	v_add_f32_e32 v245, v245, v81
	v_add_f32_e32 v82, v98, v82
	v_add_f32_e32 v242, v242, v82
	v_add_f32_e32 v83, v99, v83
	v_add_f32_e32 v243, v243, v83
	s_waitcnt lgkmcnt(2)
	v_mfma_f32_32x32x16_bf16 v[32:47], v[132:135], v[120:123], v[32:47]
	v_add_f32_e32 v84, v100, v84
	v_add_f32_e32 v240, v240, v84
	v_add_f32_e32 v85, v101, v85
	v_add_f32_e32 v241, v241, v85
	v_add_f32_e32 v86, v102, v86
	v_add_f32_e32 v238, v238, v86
	v_add_f32_e32 v87, v103, v87
	v_add_f32_e32 v239, v239, v87
	s_waitcnt lgkmcnt(1)
	v_mfma_f32_32x32x16_bf16 v[16:31], v[136:139], v[124:127], v[16:31]
	v_add_f32_e32 v88, v104, v88
	v_add_f32_e32 v236, v236, v88
	v_add_f32_e32 v89, v105, v89
	v_add_f32_e32 v237, v237, v89
	v_add_f32_e32 v90, v106, v90
	v_add_f32_e32 v234, v234, v90
	v_add_f32_e32 v91, v107, v91
	v_add_f32_e32 v235, v235, v91
	s_waitcnt lgkmcnt(0)
	v_mfma_f32_32x32x16_bf16 v[32:47], v[140:143], v[124:127], v[32:47]
	v_add_f32_e32 v92, v108, v92
	v_add_f32_e32 v232, v232, v92
	v_add_f32_e32 v93, v109, v93
	v_add_f32_e32 v233, v233, v93
	v_add_f32_e32 v94, v110, v94
	v_add_f32_e32 v230, v230, v94
	v_add_f32_e32 v95, v111, v95
	v_add_f32_e32 v231, v231, v95
	s_waitcnt lgkmcnt(0)
	s_barrier
